# GEMM tile orders: co-resident blocks (ids differing in bit 8) share neither row nor column tile
# speedup vs baseline: 1.0042x; 1.0042x over previous
; __device__ __forceinline__ int tidx() { int t = threadIdx.x; asm volatile("" : "+v"(t)); return t; }
; template <int NT>
; __device__ __forceinline__ void gemm_tile(f32x4 (&acc)[4][NT], const bf16_t* A, int lda, const bf16_t* B, int ldb, int K, bf16_t* sm) {
;     const int tid_ = tidx();
;     bf16_t* sA = sm; bf16_t* sB = sm + 128 * LDT;
;     const int tid = tid_, lane = tid & 63, wid = tid >> 6, wr = wid >> 1, wc = wid & 1;
;     const int fr = lane & 15, fq = lane >> 4;
;     const int lrow = tid >> 3, lkc = tid & 7;
;     const bf16_t* ga = A + (size_t)lrow * lda + lkc * 8;
;     const bf16_t* gb = B + (size_t)lrow * ldb + lkc * 8;
;     int sbrow[NT];
; #pragma unroll
;     for (int i = 0; i < NT; ++i) { const int g = lrow + 32 * i, W_ = 16 * NT, rem = g % W_; sbrow[i] = (g / W_) * W_ + (rem % NT) * 16 + rem / NT; }
; __device__ __forceinline__ void phase_gemm_resid(const bf16_t* A, int lda, int K, const bf16_t* W, const float* X, float* Y, float scale, bf16_t* sm) {
;     const int G = gridDim.x, NTILES = 136 * 8;
;     const int nfull = (NTILES / G) * G;
;     for (int t = blockIdx.x; t < nfull; t += G) resid_tile<4>(t >> 3, (t & 7) * 128, A, lda, K, W, X, Y, scale, sm);
.LBB0_35:
	v_mov_b32_e32 v118, v192
	v_mov_b32_e32 v36, v192
	s_and_b32 s18, s39, 7
	s_lshl_b32 s18, s18, 3
	s_bfe_u32 s19, s39, 0x30006
	s_or_b32 s18, s18, s19
	s_ashr_i32 s19, s39, 9
	s_lshl_b32 s19, s19, 6
	s_or_b32 s18, s18, s19
	v_ashrrev_i32_e32 v0, 31, v36
	v_ashrrev_i32_e32 v34, 3, v36
	v_lshrrev_b32_e32 v0, 26, v0
	v_add_u32_e32 v0, v34, v0
	v_lshrrev_b32_e32 v1, 6, v0
	v_mul_i32_i24_e32 v1, 64, v1
	v_sub_u32_e32 v1, v34, v1
	v_lshrrev_b16_sdwa v2, v196, sext(v1) dst_sel:DWORD dst_unused:UNUSED_PAD src0_sel:DWORD src1_sel:BYTE_0
	v_and_b32_e32 v2, 3, v2
	v_add_u16_e32 v2, v1, v2
	v_ashrrev_i16_sdwa v3, v197, sext(v2) dst_sel:DWORD dst_unused:UNUSED_PAD src0_sel:DWORD src1_sel:BYTE_0
	v_and_b32_e32 v2, 0xfc, v2
	v_sub_u16_e32 v1, v1, v2
	v_and_b32_e32 v0, 0x7ffffc0, v0
	v_lshlrev_b32_sdwa v1, v198, sext(v1) dst_sel:DWORD dst_unused:UNUSED_PAD src0_sel:DWORD src1_sel:BYTE_0
	v_bfe_i32 v2, v3, 0, 16
	v_add3_u32 v37, v0, v2, v1
	v_add_u32_e32 v0, 32, v34
	v_ashrrev_i32_e32 v1, 31, v0
	v_lshrrev_b32_e32 v1, 26, v1
	v_add_u32_e32 v1, v0, v1
	v_lshrrev_b32_e32 v2, 6, v1
	v_mul_i32_i24_e32 v2, 64, v2
	v_sub_u32_e32 v0, v0, v2
	v_lshrrev_b16_sdwa v2, v196, sext(v0) dst_sel:DWORD dst_unused:UNUSED_PAD src0_sel:DWORD src1_sel:BYTE_0
	v_and_b32_e32 v2, 3, v2
	v_add_u16_e32 v2, v0, v2
	v_ashrrev_i16_sdwa v3, v197, sext(v2) dst_sel:DWORD dst_unused:UNUSED_PAD src0_sel:DWORD src1_sel:BYTE_0
	v_and_b32_e32 v2, 0xfc, v2
	v_sub_u16_e32 v0, v0, v2
	v_and_b32_e32 v1, 0x7ffffc0, v1
	v_lshlrev_b32_sdwa v0, v198, sext(v0) dst_sel:DWORD dst_unused:UNUSED_PAD src0_sel:DWORD src1_sel:BYTE_0
	v_bfe_i32 v2, v3, 0, 16
	v_add3_u32 v38, v1, v2, v0
	v_add_u32_e32 v0, 64, v34
	v_ashrrev_i32_e32 v1, 31, v0
	v_lshrrev_b32_e32 v1, 26, v1
	v_add_u32_e32 v1, v0, v1
	v_lshrrev_b32_e32 v2, 6, v1
	v_mul_i32_i24_e32 v2, 64, v2
	v_sub_u32_e32 v0, v0, v2
	v_lshrrev_b16_sdwa v2, v196, sext(v0) dst_sel:DWORD dst_unused:UNUSED_PAD src0_sel:DWORD src1_sel:BYTE_0
	v_and_b32_e32 v2, 3, v2
	v_add_u16_e32 v2, v0, v2
	v_ashrrev_i16_sdwa v3, v197, sext(v2) dst_sel:DWORD dst_unused:UNUSED_PAD src0_sel:DWORD src1_sel:BYTE_0
	v_and_b32_e32 v2, 0xfc, v2
	v_sub_u16_e32 v0, v0, v2
	v_and_b32_e32 v1, 0x7ffffc0, v1
	v_lshlrev_b32_sdwa v0, v198, sext(v0) dst_sel:DWORD dst_unused:UNUSED_PAD src0_sel:DWORD src1_sel:BYTE_0
	v_bfe_i32 v2, v3, 0, 16
	v_add3_u32 v39, v1, v2, v0
	v_add_u32_e32 v0, 0x60, v34
	v_ashrrev_i32_e32 v1, 31, v0
	v_lshrrev_b32_e32 v1, 26, v1
	v_add_u32_e32 v1, v0, v1
	v_lshrrev_b32_e32 v2, 6, v1
	v_mul_i32_i24_e32 v2, 64, v2
	v_sub_u32_e32 v0, v0, v2
	s_ashr_i32 s19, s18, 31
	v_lshrrev_b16_sdwa v2, v196, sext(v0) dst_sel:DWORD dst_unused:UNUSED_PAD src0_sel:DWORD src1_sel:BYTE_0
	s_lshl_b32 s2, s39, 4
	s_lshl_b64 s[76:77], s[18:19], s97
	v_and_b32_e32 v2, 3, v2
	s_and_b32 s2, s2, 0x380
	s_bfe_u32 s19, s39, 0x10008
	s_lshl_b32 s19, s19, 9
	s_xor_b32 s2, s2, s19
	s_lshl_b64 s[78:79], s[76:77], 1
	v_add_u16_e32 v2, v0, v2
	s_add_u32 s84, s12, s78
	v_ashrrev_i16_sdwa v3, v197, sext(v2) dst_sel:DWORD dst_unused:UNUSED_PAD src0_sel:DWORD src1_sel:BYTE_0
	v_and_b32_e32 v2, 0xfc, v2
	s_addc_u32 s85, s11, s79
	s_lshl_b32 s19, s2, vcc_lo
	v_sub_u16_e32 v0, v0, v2
	s_lshl_b32 s19, s19, 1
	v_and_b32_e32 v1, 0x7ffffc0, v1
	v_lshlrev_b32_sdwa v0, v198, sext(v0) dst_sel:DWORD dst_unused:UNUSED_PAD src0_sel:DWORD src1_sel:BYTE_0
	v_bfe_i32 v2, v3, 0, 16
	v_ashrrev_i32_e32 v35, 31, v34
	s_add_u32 s76, s13, s19
	v_add3_u32 v40, v1, v2, v0
	v_lshlrev_b64 v[0:1], vcc_lo, v[34:35]
	s_addc_u32 s77, s94, 0
	v_lshlrev_b64 v[100:101], 1, v[0:1]
	v_lshlrev_b32_e32 v2, 4, v36
	v_lshl_add_u64 v[0:1], s[76:77], 0, v[100:101]
	v_and_b32_e32 v12, 0x70, v2
	v_lshl_add_u64 v[18:19], s[84:85], 0, v[100:101]
	v_lshl_add_u64 v[4:5], v[0:1], 0, v[12:13]
	s_mov_b32 s75, s87
	s_mov_b32 s83, s87
	v_lshl_add_u64 v[18:19], v[18:19], 0, v[12:13]
	v_lshl_add_u64 v[0:1], v[4:5], 0, s[86:87]
	v_lshl_add_u64 v[6:7], v[4:5], 0, s[74:75]
	v_lshl_add_u64 v[14:15], v[4:5], 0, s[82:83]
	v_lshl_add_u64 v[20:21], v[18:19], 0, s[86:87]
	v_mov_b32_e32 v250, v4
	v_mov_b32_e32 v251, v5
	s_nop 0
	s_nop 0
	s_nop 0
	s_nop 0
	v_mov_b32_e32 v248, v18
	v_mov_b32_e32 v249, v19
	v_lshl_add_u64 v[20:21], v[18:19], 0, s[74:75]
	v_lshl_add_u64 v[26:27], v[18:19], 0, s[82:83]
	s_nop 0
	v_and_b32_e32 v35, 15, v36
	v_lshrrev_b32_e32 v42, 1, v36
	v_and_or_b32 v35, v42, s3, v35
	v_mul_lo_u32 v42, v35, s89
	v_mul_lo_u32 v43, v34, s89
	v_lshl_add_u64 v[34:35], v[12:13], 0, s[78:79]
	v_and_b32_e32 v41, 48, v36
	v_and_b32_e32 v36, 0x4f, v36
	v_lshl_add_u64 v[102:103], s[42:43], 0, v[34:35]
	v_lshl_add_u64 v[104:105], s[44:45], 0, v[34:35]
	v_lshl_add_u64 v[106:107], s[46:47], 0, v[34:35]
	v_lshl_add_u64 v[108:109], s[40:41], 0, v[34:35]
	v_or_b32_e32 v34, s19, v12
	v_mov_b32_e32 v35, v13
	v_mul_u32_u24_e32 v36, 0xa0, v36
	v_mul_lo_u32 v37, v37, s89
	v_mul_lo_u32 v38, v38, s89
	v_mul_lo_u32 v39, v39, s89
	v_mul_lo_u32 v40, v40, s89
	v_lshl_add_u64 v[110:111], s[48:49], 0, v[34:35]
	v_lshl_add_u64 v[112:113], s[50:51], 0, v[34:35]
	v_lshl_add_u64 v[114:115], s[52:53], 0, v[34:35]
	v_lshl_add_u64 v[116:117], s[54:55], 0, v[34:35]
	v_mov_b32_e32 v34, 0
	v_add_u32_e32 v120, v12, v43
	v_add_u32_e32 v121, v12, v37
	v_add_u32_e32 v122, v12, v38
	v_add_u32_e32 v123, v12, v39
	v_add_u32_e32 v124, v12, v40
; template <int NT>
; __device__ __forceinline__ void gemm_tile(f32x4 (&acc)[4][NT], const bf16_t* A, int lda, const bf16_t* B, int ldb, int K, bf16_t* sm) {
;     ...
;     const bf16_t* ga = A + (size_t)lrow * lda + lkc * 8;
;     const bf16_t* gb = B + (size_t)lrow * ldb + lkc * 8;
;     int sbrow[NT];
; #pragma unroll
;     for (int i = 0; i < NT; ++i) { const int g = lrow + 32 * i, W_ = 16 * NT, rem = g % W_; sbrow[i] = (g / W_) * W_ + (rem % NT) * 16 + rem / NT; }
;     u32x4 ra0[4], rb0[NT];
; #pragma unroll
;     for (int i = 0; i < 4; ++i) ra0[i] = *(const u32x4*)(ga + (size_t)(32 * i) * lda);
; #pragma unroll
;     for (int i = 0; i < NT; ++i) rb0[i] = *(const u32x4*)(gb + (size_t)(32 * i) * ldb);
;     const int nk = K >> 6;
;     for (int kt = 0; kt < nk; ++kt) {
;         lds_barrier();
; #pragma unroll
;         for (int i = 0; i < 4; ++i) *(u32x4*)(sA + (lrow + 32 * i) * LDT + lkc * 8) = ra0[i];
; #pragma unroll
;         for (int i = 0; i < NT; ++i) *(u32x4*)(sB + sbrow[i] * LDT + lkc * 8) = rb0[i];
;         lds_barrier();
;         if (kt + 1 < nk) {
;             ga += 64; gb += 64;
; #pragma unroll
;             for (int i = 0; i < 4; ++i) ra0[i] = *(const u32x4*)(ga + (size_t)(32 * i) * lda);
; #pragma unroll
;             for (int i = 0; i < NT; ++i) rb0[i] = *(const u32x4*)(gb + (size_t)(32 * i) * ldb);
;         }
	v_add_u32_e32 v119, v41, v42
	v_add_u32_e32 v12, v41, v36
	s_mov_b32 s19, vcc_hi
	v_mov_b32_e32 v35, v34
	v_mov_b32_e32 v36, v34
	v_mov_b32_e32 v37, v34
	v_mov_b32_e32 v38, v34
	v_mov_b32_e32 v39, v34
	v_mov_b32_e32 v40, v34
	v_mov_b32_e32 v41, v34
	v_mov_b32_e32 v42, v34
	v_mov_b32_e32 v43, v34
	v_mov_b32_e32 v44, v34
	v_mov_b32_e32 v45, v34
	v_mov_b32_e32 v46, v34
	v_mov_b32_e32 v47, v34
	v_mov_b32_e32 v48, v34
	v_mov_b32_e32 v49, v34
	v_mov_b32_e32 v50, v34
	v_mov_b32_e32 v51, v34
	v_mov_b32_e32 v52, v34
	v_mov_b32_e32 v53, v34
	v_mov_b32_e32 v54, v34
	v_mov_b32_e32 v55, v34
	v_mov_b32_e32 v56, v34
	v_mov_b32_e32 v57, v34
	v_mov_b32_e32 v58, v34
	v_mov_b32_e32 v59, v34
	v_mov_b32_e32 v60, v34
	v_mov_b32_e32 v61, v34
	v_mov_b32_e32 v62, v34
	v_mov_b32_e32 v63, v34
	v_mov_b32_e32 v64, v34
	v_mov_b32_e32 v65, v34
	v_mov_b32_e32 v66, v34
	v_mov_b32_e32 v67, v34
	v_mov_b32_e32 v68, v34
	v_mov_b32_e32 v69, v34
	v_mov_b32_e32 v70, v34
	v_mov_b32_e32 v71, v34
	v_mov_b32_e32 v72, v34
	v_mov_b32_e32 v73, v34
	v_mov_b32_e32 v74, v34
	v_mov_b32_e32 v75, v34
	v_mov_b32_e32 v76, v34
	v_mov_b32_e32 v77, v34
	v_mov_b32_e32 v78, v34
	v_mov_b32_e32 v79, v34
	v_mov_b32_e32 v80, v34
	v_mov_b32_e32 v81, v34
	v_mov_b32_e32 v82, v34
	v_mov_b32_e32 v83, v34
	v_mov_b32_e32 v84, v34
	v_mov_b32_e32 v85, v34
	v_mov_b32_e32 v86, v34
	v_mov_b32_e32 v87, v34
	v_mov_b32_e32 v88, v34
	v_mov_b32_e32 v89, v34
	v_mov_b32_e32 v90, v34
	v_mov_b32_e32 v91, v34
	v_mov_b32_e32 v92, v34
	v_mov_b32_e32 v93, v34
	v_mov_b32_e32 v94, v34
	v_mov_b32_e32 v95, v34
	v_mov_b32_e32 v96, v34
	v_mov_b32_e32 v97, v34
	v_writelane_b32 v234, s90, 0
	v_writelane_b32 v234, s91, 1
	v_writelane_b32 v234, s92, 2
	v_writelane_b32 v234, s93, 3
	v_writelane_b32 v234, s94, 4
	v_writelane_b32 v234, s95, 5
	v_bfe_u32 v160, v192, 3, 3
	v_and_b32_e32 v161, 7, v192
	v_xor_b32_e32 v161, v160, v161
	v_lshlrev_b32_e32 v161, 4, v161
	v_lshrrev_b32_e32 v162, 6, v192
	v_lshl_add_u32 v163, v162, 5, v160
	s_lshl_b32 s95, s96, 1
	v_mul_u32_u24_e32 v163, s95, v163
	v_add_u32_e32 v236, v163, v161
	s_lshl_b32 s95, s96, 4
	s_sub_u32 s95, s95, 0x400
	v_add_u32_e32 v237, s95, v236
	v_add_u32_e32 v238, s95, v237
	v_add_u32_e32 v239, s95, v238
	v_lshrrev_b32_e32 v163, 7, v192
	v_bfe_u32 v162, v192, 6, 1
	v_lshlrev_b32_e32 v163, 6, v163
	v_lshl_add_u32 v163, v160, 2, v163
	v_lshl_add_u32 v163, v162, 1, v163
	s_lshl_b32 s95, s96, 1
	v_mul_u32_u24_e32 v163, s95, v163
	v_add_u32_e32 v240, v163, v161
	s_mul_i32 s95, s96, 64
	s_sub_u32 s95, s95, 0x400
	v_add_u32_e32 v241, s95, v240
	s_mul_i32 s95, s96, 62
	s_add_u32 s95, s95, 0x400
	v_subrev_u32_e32 v242, s95, v241
	s_mul_i32 s95, s96, 64
	s_sub_u32 s95, s95, 0x400
	v_add_u32_e32 v243, s95, v242
	v_and_b32_e32 v160, 15, v192
	v_bfe_u32 v161, v192, 4, 2
	v_and_b32_e32 v162, 7, v160
	v_xor_b32_e32 v161, v161, v162
	v_lshlrev_b32_e32 v161, 4, v161
	v_lshl_add_u32 v161, v160, 7, v161
	v_lshrrev_b32_e32 v162, 7, v192
	v_lshl_add_u32 v244, v162, 13, v161
	v_bfe_u32 v162, v192, 6, 1
	v_lshl_add_u32 v246, v162, 13, v161
	v_add_u32_e32 v246, 0x4000, v246
	v_xor_b32_e32 v245, 64, v244
	v_xor_b32_e32 v247, 64, v246
	v_lshrrev_b32_e32 v160, 6, v192
	s_nop 0
	v_readfirstlane_b32 s94, v160
	v_readfirstlane_b32 s90, v248
	v_readfirstlane_b32 s91, v249
	v_readfirstlane_b32 s92, v250
	v_readfirstlane_b32 s93, v251
	s_lshl_b32 s95, s96, 4
	s_mul_i32 s95, s94, s95
	s_sub_u32 s90, s90, s95
	s_subb_u32 s91, s91, 0
	s_lshl_b32 s95, s96, 4
	s_mul_i32 s95, s94, s95
	s_sub_u32 s92, s92, s95
	s_subb_u32 s93, s93, 0
	s_lshl_b32 s94, s94, 10
	s_waitcnt lgkmcnt(0)
	s_barrier
	s_lshl_b32 s95, s94, 2
	s_add_u32 m0, s95, 0x0
	s_nop 0
	global_load_lds_dwordx4 v236, s[90:91]
	global_load_lds_dwordx4 v237, s[90:91] offset:1024
	global_load_lds_dwordx4 v238, s[90:91] offset:2048
	global_load_lds_dwordx4 v239, s[90:91] offset:3072
	s_mul_i32 s95, s94, 4
	s_add_u32 m0, s95, 0x4000
	s_nop 0
	global_load_lds_dwordx4 v240, s[92:93]
	global_load_lds_dwordx4 v241, s[92:93] offset:1024
	global_load_lds_dwordx4 v242, s[92:93] offset:2048
	global_load_lds_dwordx4 v243, s[92:93] offset:3072
	s_add_u32 s90, s90, 0x80
	s_addc_u32 s91, s91, 0
	s_add_u32 s92, s92, 0x80
	s_addc_u32 s93, s93, 0
	s_waitcnt vmcnt(0)
	s_barrier
	s_lshl_b32 s95, s94, 2
	s_add_u32 m0, s95, 0x8000
	s_nop 0
	global_load_lds_dwordx4 v236, s[90:91]
	global_load_lds_dwordx4 v237, s[90:91] offset:1024
	global_load_lds_dwordx4 v238, s[90:91] offset:2048
	global_load_lds_dwordx4 v239, s[90:91] offset:3072
	s_mul_i32 s95, s94, 4
	s_add_u32 m0, s95, 0xc000
	s_nop 0
	global_load_lds_dwordx4 v240, s[92:93]
	global_load_lds_dwordx4 v241, s[92:93] offset:1024
	global_load_lds_dwordx4 v242, s[92:93] offset:2048
	global_load_lds_dwordx4 v243, s[92:93] offset:3072
	s_add_u32 s90, s90, 0x80
	s_addc_u32 s91, s91, 0
	s_add_u32 s92, s92, 0x80
	s_addc_u32 s93, s93, 0
	ds_read_b128 v[126:129], v244 offset:0
	ds_read_b128 v[130:133], v244 offset:2048
	ds_read_b128 v[134:137], v244 offset:4096
	ds_read_b128 v[138:141], v244 offset:6144
	ds_read_b128 v[142:145], v246 offset:0
	ds_read_b128 v[146:149], v246 offset:2048
	ds_read_b128 v[152:155], v246 offset:4096
	ds_read_b128 v[156:159], v246 offset:6144
	s_lshr_b32 s95, s96, 7
	s_add_i32 s95, s95, -2
	s_cmp_eq_u32 s95, 0
	s_cbranch_scc1 .Lgemm_x36

; __device__ __forceinline__ void phase_proj(const bf16_t* xb, const bf16_t* W, bf16_t* P, bf16_t* sm) {
;     ...
;     for (int t = blockIdx.x; t < 136 * 37; t += gridDim.x) {
;         const int tm = t / 37, tn = t % 37;
;         f32x4 acc[4][4]; zero_acc<4>(acc);
;         gemm_tile<4>(acc, xb + (size_t)tm * 128 * 1024, 1024, W + (size_t)tn * 128 * 1024, 1024, 1024, sm);
.LBB0_464:
	v_mov_b32_e32 v38, v192
	s_lshr_b32 s2, s13, 9
	s_and_b32 s14, s13, 7
	s_bfe_u32 s15, s13, 0x60003
	s_cmp_eq_u32 s2, 9
	s_cselect_b32 s18, 53, 64
	s_mul_i32 s14, s14, s18
	s_lshl_b32 s2, s2, 9
	s_add_i32 s2, s2, s14
	s_add_i32 s2, s2, s15
	s_mul_i32 s14, s2, 0x7879
	s_lshr_b32 s14, s14, 24
	s_mul_i32 s15, s14, 0x220
	s_sub_i32 s15, s2, s15
	s_lshl_b32 s18, s14, 2
	s_and_b32 s19, s15, 3
	s_add_i32 s18, s18, s19
	s_bfe_u32 s19, s15, 0x10005
	s_lshl_b32 s19, s19, 1
	s_xor_b32 s18, s18, s19
	s_lshr_b32 s14, s15, 2
	s_cmpk_lt_u32 s2, 0x1320
	s_cbranch_scc1 .Lproj_map_done
	s_sub_i32 s14, s2, 0x1320
	s_movk_i32 s18, 36

; __device__ __forceinline__ void phase_merge(const bf16_t* G, const bf16_t* BO, const bf16_t* Wb, bf16_t* M, bf16_t* sm) {
;     ...
;     for (int t = blockIdx.x; t < 136 * 16; t += gridDim.x) {
;         const int tm = t >> 4, tn = t & 15;
;         const int cbase = tn * 64 + wc * 32 + fq * 8;
;         f32x4 accm[4][2]; zero_acc<2>(accm);
; #pragma unroll 1
;         for (int i = 0; i < 4; ++i) {
;             f32x4 accb[4][2]; zero_acc<2>(accb);
;             const int koff = i * 512, kk = i < 3 ? 512 : 256;
;             gemm_tile<2>(accb, BO + (size_t)tm * 128 * 1792 + koff, 1792, Wb + (size_t)tn * 64 * 1792 + koff, 1792, kk, sm);
.LBB0_474:
	s_bfe_u32 s2, s42, 0x30003
	s_and_b32 s24, s42, 1
	s_lshl_b32 s24, s24, 3
	s_or_b32 s2, s2, s24
	s_bfe_u32 s24, s42, 0x10008
	s_lshl_b32 s24, s24, 2
	s_xor_b32 s2, s2, s24
	s_and_b32 s24, s42, 15
	s_cmpk_lt_i32 s42, 0x800
	s_cselect_b32 s2, s2, s24
	s_mov_b32 s40, s2
	s_mul_i32 s2, s2, 0x38000
	s_add_u32 s22, s58, s2
	s_addc_u32 s23, s59, 0
	s_lshr_b32 s2, s43, 9
	s_lshl_b32 s2, s2, 5
	s_bfe_u32 s24, s43, 0x20001
	s_lshl_b32 s24, s24, 3
	s_or_b32 s2, s2, s24
	s_bfe_u32 s24, s43, 0x30006
	s_or_b32 s2, s2, s24
	s_ashr_i32 s24, s43, 4
	s_cmpk_lt_i32 s43, 0x800
	s_cselect_b32 s2, s2, s24
	s_mov_b32 s24, s40
	s_mul_i32 s40, s2, 0x70000
	s_mul_hi_i32 s25, s2, 0x70000
	s_add_u32 s44, s11, s40
	v_lshl_or_b32 v66, s24, 6, v67
	s_addc_u32 s45, s12, s25
	s_mul_i32 s24, s24, 0x38000
	s_add_u32 s46, s13, s24
	v_lshl_add_u32 v64, s2, 7, v114
	s_addc_u32 s47, s39, 0
	v_or_b32_e32 v62, 16, v64
	v_or_b32_e32 v60, 32, v64
	v_or_b32_e32 v58, 48, v64
	v_lshlrev_b32_e32 v12, 1, v66
	v_ashrrev_i32_e32 v65, 31, v64
	v_ashrrev_i32_e32 v63, 31, v62
	v_ashrrev_i32_e32 v61, 31, v60
	v_ashrrev_i32_e32 v59, 31, v58
	s_add_u32 s24, s58, s40
	v_mov_b32_e32 v115, 0
	v_lshl_add_u64 v[76:77], s[14:15], 0, v[12:13]
	v_lshlrev_b64 v[78:79], 13, v[64:65]
	v_lshlrev_b64 v[80:81], 13, v[62:63]
	v_lshlrev_b64 v[90:91], 13, v[60:61]
	v_lshlrev_b64 v[92:93], 13, v[58:59]
	s_addc_u32 s25, s59, s25
	s_mov_b32 s48, 0
	v_mov_b32_e32 v75, 0
	v_mov_b32_e32 v73, 0
	v_mov_b32_e32 v71, 0
	v_mov_b32_e32 v69, 0
	v_mov_b32_e32 v74, v115
	v_mov_b32_e32 v72, v115
	v_mov_b32_e32 v70, v115
	v_mov_b32_e32 v68, v115
	v_mov_b32_e32 v89, 0
	v_mov_b32_e32 v87, 0
	v_mov_b32_e32 v85, 0
	v_mov_b32_e32 v83, 0
	v_mov_b32_e32 v88, v115
	v_mov_b32_e32 v86, v115
	v_mov_b32_e32 v84, v115
	v_mov_b32_e32 v82, v115
	v_mov_b32_e32 v101, 0
	v_mov_b32_e32 v99, 0
	v_mov_b32_e32 v97, 0
	v_mov_b32_e32 v95, 0
	v_mov_b32_e32 v100, v115
	v_mov_b32_e32 v98, v115
	v_mov_b32_e32 v96, v115
	v_mov_b32_e32 v94, v115
	v_mov_b32_e32 v109, 0
	v_mov_b32_e32 v107, 0
	v_mov_b32_e32 v105, 0
	v_mov_b32_e32 v103, 0
	v_mov_b32_e32 v108, v115
	v_mov_b32_e32 v106, v115
	v_mov_b32_e32 v104, v115
	v_mov_b32_e32 v102, v115

; template <int NT>
; __device__ __forceinline__ void gemm_tile(f32x4 (&acc)[4][NT], const bf16_t* A, int lda, const bf16_t* B, int ldb, int K, bf16_t* sm) {
;     ...
;     const int tid = tid_, lane = tid & 63, wid = tid >> 6, wr = wid >> 1, wc = wid & 1;
;     const int fr = lane & 15, fq = lane >> 4;
;     const int lrow = tid >> 3, lkc = tid & 7;
;     const bf16_t* ga = A + (size_t)lrow * lda + lkc * 8;
;     const bf16_t* gb = B + (size_t)lrow * ldb + lkc * 8;
;     int sbrow[NT];
; #pragma unroll
;     for (int i = 0; i < NT; ++i) { const int g = lrow + 32 * i, W_ = 16 * NT, rem = g % W_; sbrow[i] = (g / W_) * W_ + (rem % NT) * 16 + rem / NT; }
;     u32x4 ra0[4], rb0[NT];
; #pragma unroll
;     for (int i = 0; i < 4; ++i) ra0[i] = *(const u32x4*)(ga + (size_t)(32 * i) * lda);
; #pragma unroll
;     for (int i = 0; i < NT; ++i) rb0[i] = *(const u32x4*)(gb + (size_t)(32 * i) * ldb);
; __device__ __forceinline__ void phase_ffn_in(const bf16_t* xb, const bf16_t* W, bf16_t* H, bf16_t* sm) {
;     ...
;     for (int t = blockIdx.x; t < 136 * 32; t += gridDim.x) {
;         const int tm = t >> 5, tn = t & 31;
;         f32x4 acc[4][4]; zero_acc<4>(acc);
;         gemm_tile<4>(acc, xb + (size_t)tm * 128 * 1024, 1024, W + (size_t)tn * 128 * 1024, 1024, 1024, sm);
.LBB0_1479:
	v_mov_b32_e32 v38, v192
	s_ashr_i32 s18, s11, 5
	v_ashrrev_i32_e32 v0, 31, v38
	v_ashrrev_i32_e32 v30, 3, v38
	v_lshrrev_b32_e32 v0, 26, v0
	v_add_u32_e32 v0, v30, v0
	v_lshrrev_b32_e32 v1, 6, v0
	v_mul_i32_i24_e32 v1, 64, v1
	v_sub_u32_e32 v1, v30, v1
	v_lshrrev_b16_sdwa v2, v196, sext(v1) dst_sel:DWORD dst_unused:UNUSED_PAD src0_sel:DWORD src1_sel:BYTE_0
	v_and_b32_e32 v2, 3, v2
	v_add_u16_e32 v2, v1, v2
	v_ashrrev_i16_sdwa v3, v197, sext(v2) dst_sel:DWORD dst_unused:UNUSED_PAD src0_sel:DWORD src1_sel:BYTE_0
	v_and_b32_e32 v2, 0xfc, v2
	v_sub_u16_e32 v1, v1, v2
	v_and_b32_e32 v0, 0x7ffffc0, v0
	v_lshlrev_b32_sdwa v1, v198, sext(v1) dst_sel:DWORD dst_unused:UNUSED_PAD src0_sel:DWORD src1_sel:BYTE_0
	v_bfe_i32 v2, v3, 0, 16
	v_add3_u32 v39, v0, v2, v1
	v_add_u32_e32 v0, 32, v30
	v_ashrrev_i32_e32 v1, 31, v0
	v_lshrrev_b32_e32 v1, 26, v1
	v_add_u32_e32 v1, v0, v1
	v_lshrrev_b32_e32 v2, 6, v1
	v_mul_i32_i24_e32 v2, 64, v2
	v_sub_u32_e32 v0, v0, v2
	v_lshrrev_b16_sdwa v2, v196, sext(v0) dst_sel:DWORD dst_unused:UNUSED_PAD src0_sel:DWORD src1_sel:BYTE_0
	v_and_b32_e32 v2, 3, v2
	v_add_u16_e32 v2, v0, v2
	v_ashrrev_i16_sdwa v3, v197, sext(v2) dst_sel:DWORD dst_unused:UNUSED_PAD src0_sel:DWORD src1_sel:BYTE_0
	v_and_b32_e32 v2, 0xfc, v2
	v_sub_u16_e32 v0, v0, v2
	v_and_b32_e32 v1, 0x7ffffc0, v1
	v_lshlrev_b32_sdwa v0, v198, sext(v0) dst_sel:DWORD dst_unused:UNUSED_PAD src0_sel:DWORD src1_sel:BYTE_0
	v_bfe_i32 v2, v3, 0, 16
	v_add3_u32 v40, v1, v2, v0
	v_add_u32_e32 v0, 64, v30
	v_ashrrev_i32_e32 v1, 31, v0
	v_lshrrev_b32_e32 v1, 26, v1
	v_add_u32_e32 v1, v0, v1
	v_lshrrev_b32_e32 v2, 6, v1
	v_mul_i32_i24_e32 v2, 64, v2
	v_sub_u32_e32 v0, v0, v2
	v_lshrrev_b16_sdwa v2, v196, sext(v0) dst_sel:DWORD dst_unused:UNUSED_PAD src0_sel:DWORD src1_sel:BYTE_0
	v_and_b32_e32 v2, 3, v2
	v_add_u16_e32 v2, v0, v2
	v_ashrrev_i16_sdwa v3, v197, sext(v2) dst_sel:DWORD dst_unused:UNUSED_PAD src0_sel:DWORD src1_sel:BYTE_0
	v_and_b32_e32 v2, 0xfc, v2
	v_sub_u16_e32 v0, v0, v2
	v_and_b32_e32 v1, 0x7ffffc0, v1
	v_lshlrev_b32_sdwa v0, v198, sext(v0) dst_sel:DWORD dst_unused:UNUSED_PAD src0_sel:DWORD src1_sel:BYTE_0
	v_bfe_i32 v2, v3, 0, 16
	s_waitcnt lgkmcnt(0)
	v_add3_u32 v41, v1, v2, v0
	v_add_u32_e32 v0, 0x60, v30
	v_ashrrev_i32_e32 v1, 31, v0
	v_lshrrev_b32_e32 v1, 26, v1
	v_add_u32_e32 v1, v0, v1
	v_lshrrev_b32_e32 v2, 6, v1
	v_mul_i32_i24_e32 v2, 64, v2
	v_sub_u32_e32 v0, v0, v2
	v_lshrrev_b16_sdwa v2, v196, sext(v0) dst_sel:DWORD dst_unused:UNUSED_PAD src0_sel:DWORD src1_sel:BYTE_0
	s_and_b32 s2, s10, 31
	s_bfe_u32 s12, s10, 0x10008
	s_lshl_b32 s12, s12, 3
	s_xor_b32 s2, s2, s12
	s_ashr_i32 s19, s18, 31
	v_and_b32_e32 v2, 3, v2
	s_lshl_b32 s86, s2, 18
	s_mov_b32 s12, s2
	s_lshl_b64 s[22:23], s[18:19], 18
	v_add_u16_e32 v2, v0, v2
	s_add_u32 s24, s80, s22
	v_ashrrev_i16_sdwa v3, v197, sext(v2) dst_sel:DWORD dst_unused:UNUSED_PAD src0_sel:DWORD src1_sel:BYTE_0
	v_and_b32_e32 v2, 0xfc, v2
	s_addc_u32 s25, s81, s23
	s_lshl_b32 s2, s12, 18
	v_sub_u16_e32 v0, v0, v2
	s_add_u32 s40, s16, s2
	v_and_b32_e32 v1, 0x7ffffc0, v1
	v_lshlrev_b32_sdwa v0, v198, sext(v0) dst_sel:DWORD dst_unused:UNUSED_PAD src0_sel:DWORD src1_sel:BYTE_0
	v_bfe_i32 v2, v3, 0, 16
	v_ashrrev_i32_e32 v31, 31, v30
	s_addc_u32 s41, s17, 0
	v_add3_u32 v42, v1, v2, v0
	v_lshlrev_b64 v[32:33], 11, v[30:31]
	v_lshlrev_b32_e32 v2, 4, v38
	v_lshl_add_u64 v[0:1], s[40:41], 0, v[32:33]
	v_and_b32_e32 v12, 0x70, v2
	v_lshl_add_u64 v[8:9], v[0:1], 0, v[12:13]
	v_add_co_u32_e32 v0, vcc, s7, v8
	v_lshl_add_u64 v[18:19], s[24:25], 0, v[32:33]
	s_nop 0
	v_addc_co_u32_e32 v1, vcc, 0, v9, vcc
	v_add_co_u32_e32 v10, vcc, s37, v8
	v_lshl_add_u64 v[26:27], v[18:19], 0, v[12:13]
	s_nop 0
	v_addc_co_u32_e32 v11, vcc, 0, v9, vcc
	v_add_co_u32_e32 v14, vcc, s73, v8
	v_mov_b32_e32 v250, v8
	v_mov_b32_e32 v251, v9
	s_nop 0
	v_addc_co_u32_e32 v15, vcc, 0, v9, vcc
	v_add_co_u32_e32 v18, vcc, s7, v26
	s_nop 0
	v_addc_co_u32_e32 v19, vcc, 0, v27, vcc
	v_add_co_u32_e32 v28, vcc, s37, v26
	v_mov_b32_e32 v248, v26
	v_mov_b32_e32 v249, v27
	s_nop 0
	v_addc_co_u32_e32 v29, vcc, 0, v27, vcc
	v_add_co_u32_e32 v34, vcc, s73, v26
	v_and_b32_e32 v31, 15, v38
	s_nop 0
	v_addc_co_u32_e32 v35, vcc, 0, v27, vcc
	s_nop 0
	v_lshrrev_b32_e32 v44, 1, v38
	v_and_or_b32 v31, v44, s3, v31
	v_mul_lo_u32 v44, v31, s89
	v_mul_lo_u32 v45, v30, s89
	v_lshl_add_u64 v[30:31], s[22:23], 0, v[32:33]
	v_or_b32_e32 v30, v30, v12
	v_lshl_add_u64 v[98:99], s[58:59], 0, v[30:31]
	v_lshl_add_u64 v[30:31], s[86:87], 0, v[32:33]
	v_and_b32_e32 v43, 48, v38
	v_and_b32_e32 v38, 0x4f, v38
	v_or_b32_e32 v30, v30, v12
	v_mul_u32_u24_e32 v38, 0xa0, v38
	v_mul_lo_u32 v39, v39, s89
	v_mul_lo_u32 v40, v40, s89
	v_mul_lo_u32 v41, v41, s89
	v_mul_lo_u32 v42, v42, s89
	v_lshl_add_u64 v[100:101], s[16:17], 0, v[30:31]
	v_mov_b32_e32 v30, 0
	s_mov_b64 s[22:23], 0
	v_add_u32_e32 v105, v12, v45
	v_add_u32_e32 v106, v12, v39
	v_add_u32_e32 v107, v12, v40
	v_add_u32_e32 v108, v12, v41
; template <int NT>
; __device__ __forceinline__ void gemm_tile(f32x4 (&acc)[4][NT], const bf16_t* A, int lda, const bf16_t* B, int ldb, int K, bf16_t* sm) {
;     ...
;     u32x4 ra0[4], rb0[NT];
; #pragma unroll
;     for (int i = 0; i < 4; ++i) ra0[i] = *(const u32x4*)(ga + (size_t)(32 * i) * lda);
; #pragma unroll
;     for (int i = 0; i < NT; ++i) rb0[i] = *(const u32x4*)(gb + (size_t)(32 * i) * ldb);
;     const int nk = K >> 6;
;     for (int kt = 0; kt < nk; ++kt) {
;         lds_barrier();
; #pragma unroll
;         for (int i = 0; i < 4; ++i) *(u32x4*)(sA + (lrow + 32 * i) * LDT + lkc * 8) = ra0[i];
; #pragma unroll
;         for (int i = 0; i < NT; ++i) *(u32x4*)(sB + sbrow[i] * LDT + lkc * 8) = rb0[i];
;         lds_barrier();
;         if (kt + 1 < nk) {
;             ga += 64; gb += 64;
; #pragma unroll
;             for (int i = 0; i < 4; ++i) ra0[i] = *(const u32x4*)(ga + (size_t)(32 * i) * lda);
; #pragma unroll
;             for (int i = 0; i < NT; ++i) rb0[i] = *(const u32x4*)(gb + (size_t)(32 * i) * ldb);
;         }
;         __builtin_amdgcn_sched_barrier(0);
;         gemm_compute<NT>(acc, sA, sB, wr, wc, fr, fq);
	v_add_u32_e32 v109, v12, v42
	v_add_u32_e32 v104, v43, v44
	v_add_u32_e32 v12, v43, v38
	v_mov_b32_e32 v31, v30
	v_mov_b32_e32 v32, v30
	v_mov_b32_e32 v33, v30
	v_mov_b32_e32 v38, v30
	v_mov_b32_e32 v39, v30
	v_mov_b32_e32 v40, v30
	v_mov_b32_e32 v41, v30
	v_mov_b32_e32 v42, v30
	v_mov_b32_e32 v43, v30
	v_mov_b32_e32 v44, v30
	v_mov_b32_e32 v45, v30
	v_mov_b32_e32 v46, v30
	v_mov_b32_e32 v47, v30
	v_mov_b32_e32 v48, v30
	v_mov_b32_e32 v49, v30
	v_mov_b32_e32 v50, v30
	v_mov_b32_e32 v51, v30
	v_mov_b32_e32 v52, v30
	v_mov_b32_e32 v53, v30
	v_mov_b32_e32 v54, v30
	v_mov_b32_e32 v55, v30
	v_mov_b32_e32 v56, v30
	v_mov_b32_e32 v57, v30
	v_mov_b32_e32 v58, v30
	v_mov_b32_e32 v59, v30
	v_mov_b32_e32 v60, v30
	v_mov_b32_e32 v61, v30
	v_mov_b32_e32 v62, v30
	v_mov_b32_e32 v63, v30
	v_mov_b32_e32 v64, v30
	v_mov_b32_e32 v65, v30
	v_mov_b32_e32 v66, v30
	v_mov_b32_e32 v67, v30
	v_mov_b32_e32 v68, v30
	v_mov_b32_e32 v69, v30
	v_mov_b32_e32 v70, v30
	v_mov_b32_e32 v71, v30
	v_mov_b32_e32 v72, v30
	v_mov_b32_e32 v73, v30
	v_mov_b32_e32 v74, v30
	v_mov_b32_e32 v75, v30
	v_mov_b32_e32 v76, v30
	v_mov_b32_e32 v77, v30
	v_mov_b32_e32 v78, v30
	v_mov_b32_e32 v79, v30
	v_mov_b32_e32 v80, v30
	v_mov_b32_e32 v81, v30
	v_mov_b32_e32 v82, v30
	v_mov_b32_e32 v83, v30
	v_mov_b32_e32 v84, v30
	v_mov_b32_e32 v85, v30
	v_mov_b32_e32 v86, v30
	v_mov_b32_e32 v87, v30
	v_mov_b32_e32 v88, v30
	v_mov_b32_e32 v89, v30
	v_mov_b32_e32 v90, v30
	v_mov_b32_e32 v91, v30
	v_mov_b32_e32 v92, v30
	v_mov_b32_e32 v93, v30
	v_mov_b32_e32 v94, v30
	v_mov_b32_e32 v95, v30
	v_mov_b32_e32 v96, v30
	v_mov_b32_e32 v97, v30
	v_writelane_b32 v234, s90, 0
	v_writelane_b32 v234, s91, 1
	v_writelane_b32 v234, s92, 2
	v_writelane_b32 v234, s93, 3
	v_writelane_b32 v234, s94, 4
	v_writelane_b32 v234, s95, 5
	v_bfe_u32 v160, v192, 3, 3
	v_and_b32_e32 v161, 7, v192
	v_xor_b32_e32 v161, v160, v161
	v_lshlrev_b32_e32 v161, 4, v161
	v_lshrrev_b32_e32 v162, 6, v192
	v_lshl_add_u32 v163, v162, 5, v160
	v_mul_u32_u24_e32 v163, 0x800, v163
	v_add_u32_e32 v236, v163, v161
	v_add_u32_e32 v237, 0x3c00, v236
	v_add_u32_e32 v238, 0x3c00, v237
	v_add_u32_e32 v239, 0x3c00, v238
	v_lshrrev_b32_e32 v163, 7, v192
	v_bfe_u32 v162, v192, 6, 1
	v_lshlrev_b32_e32 v163, 6, v163
	v_lshl_add_u32 v163, v160, 2, v163
	v_lshl_add_u32 v163, v162, 1, v163
	v_mul_u32_u24_e32 v163, 0x800, v163
	v_add_u32_e32 v240, v163, v161
	v_add_u32_e32 v241, 0xfc00, v240
	v_subrev_u32_e32 v242, 0xfc00, v241
	v_add_u32_e32 v243, 0xfc00, v242
	v_and_b32_e32 v160, 15, v192
	v_bfe_u32 v161, v192, 4, 2
	v_and_b32_e32 v162, 7, v160
	v_xor_b32_e32 v161, v161, v162
	v_lshlrev_b32_e32 v161, 4, v161
	v_lshl_add_u32 v161, v160, 7, v161
	v_lshrrev_b32_e32 v162, 7, v192
	v_lshl_add_u32 v244, v162, 13, v161
	v_bfe_u32 v162, v192, 6, 1
	v_lshl_add_u32 v246, v162, 13, v161
	v_add_u32_e32 v246, 0x4000, v246
	v_xor_b32_e32 v245, 64, v244
	v_xor_b32_e32 v247, 64, v246
	v_lshrrev_b32_e32 v160, 6, v192
	s_nop 0
	v_readfirstlane_b32 s94, v160
	v_readfirstlane_b32 s90, v248
	v_readfirstlane_b32 s91, v249
	v_readfirstlane_b32 s92, v250
	v_readfirstlane_b32 s93, v251
	s_mul_i32 s95, s94, 0x4000
	s_sub_u32 s90, s90, s95
	s_subb_u32 s91, s91, 0
	s_mul_i32 s95, s94, 0x4000
	s_sub_u32 s92, s92, s95
	s_subb_u32 s93, s93, 0
	s_lshl_b32 s94, s94, 10
	s_waitcnt lgkmcnt(0)
	s_barrier
	s_lshl_b32 s95, s94, 2
	s_add_u32 m0, s95, 0x0
	s_nop 0
	global_load_lds_dwordx4 v236, s[90:91]
	global_load_lds_dwordx4 v237, s[90:91] offset:1024
	global_load_lds_dwordx4 v238, s[90:91] offset:2048
	global_load_lds_dwordx4 v239, s[90:91] offset:3072
	s_mul_i32 s95, s94, 4
	s_add_u32 m0, s95, 0x4000
	s_nop 0
	global_load_lds_dwordx4 v240, s[92:93]
	global_load_lds_dwordx4 v241, s[92:93] offset:1024
	global_load_lds_dwordx4 v242, s[92:93] offset:2048
	global_load_lds_dwordx4 v243, s[92:93] offset:3072
	s_add_u32 s90, s90, 0x80
	s_addc_u32 s91, s91, 0
	s_add_u32 s92, s92, 0x80
	s_addc_u32 s93, s93, 0
	s_waitcnt vmcnt(0)
	s_barrier
	s_lshl_b32 s95, s94, 2
	s_add_u32 m0, s95, 0x8000
	s_nop 0
	global_load_lds_dwordx4 v236, s[90:91]
	global_load_lds_dwordx4 v237, s[90:91] offset:1024
	global_load_lds_dwordx4 v238, s[90:91] offset:2048
	global_load_lds_dwordx4 v239, s[90:91] offset:3072
	s_mul_i32 s95, s94, 4
	s_add_u32 m0, s95, 0xc000
	s_nop 0
	global_load_lds_dwordx4 v240, s[92:93]
	global_load_lds_dwordx4 v241, s[92:93] offset:1024
	global_load_lds_dwordx4 v242, s[92:93] offset:2048
	global_load_lds_dwordx4 v243, s[92:93] offset:3072
	s_add_u32 s90, s90, 0x80
	s_addc_u32 s91, s91, 0
	s_add_u32 s92, s92, 0x80
	s_addc_u32 s93, s93, 0
	ds_read_b128 v[110:113], v244 offset:0
	ds_read_b128 v[114:117], v244 offset:2048
	ds_read_b128 v[118:121], v244 offset:4096
	ds_read_b128 v[122:125], v244 offset:6144
	ds_read_b128 v[126:129], v246 offset:0
	ds_read_b128 v[130:133], v246 offset:2048
	ds_read_b128 v[134:137], v246 offset:4096
	ds_read_b128 v[138:141], v246 offset:6144
	s_movk_i32 s95, 0x6
	s_cmp_eq_u32 s95, 0
	s_cbranch_scc1 .Lgemm_x1480
